# RET: pipelined LDS reads + K/V prefetch loads moved into the QK segment; vmcnt(3) loop top
# speedup vs baseline: 1.0042x; 1.0042x over previous
; __device__ __forceinline__ void ret_phase(const Params& p, unsigned char* shm, float* rssq) {
;     ...
;     for (int ch = 0; ch < 64; ++ch) {
;         __syncthreads();
;         cg2[0] = pg[0]; cg2[1] = pg[1];
; #pragma unroll
;         for (int j = 0; j < 4; ++j) {
;             *(u32x4*)(Qs + (j * 16 + (tid >> 5)) * QS + (tid & 31) * 8) = pq[j];
;             *(u32x4*)(Ks + lane * QS + wid * 32 + j * 8) = pk[j];
;             const unsigned kw[4] = {pk[j].x, pk[j].y, pk[j].z, pk[j].w};
; #pragma unroll
;             for (int i = 0; i < 4; ++i) {
;                 KTs[(wid * 32 + j * 8 + 2 * i) * TS + lane] = (bf16_t)(kw[i] & 0xffffu);
;                 KTs[(wid * 32 + j * 8 + 2 * i + 1) * TS + lane] = (bf16_t)(kw[i] >> 16);
;             }
;         }
;         { const unsigned vw[4] = {pv.x, pv.y, pv.z, pv.w};
; #pragma unroll
;           for (int i = 0; i < 4; ++i) { VTs[(wid * 8 + 2 * i) * TS + lane] = (bf16_t)(vw[i] & 0xffffu); VTs[(wid * 8 + 2 * i + 1) * TS + lane] = (bf16_t)(vw[i] >> 16); } }
; #pragma unroll
;         for (int ei = 0; ei < 4; ++ei)
; #pragma unroll
;             for (int di = 0; di < 2; ++di) { u32x2 w; w.x = cvt_pk_bf16(R[ei][di][0], R[ei][di][1]); w.y = cvt_pk_bf16(R[ei][di][2], R[ei][di][3]);
;                 *(u32x2*)(RTs + (16 * ei + fr) * QS + wid * 32 + 16 * di + 4 * fq) = w; }
;         if (ch + 1 < 64) {
;             const size_t adv = (size_t)(ch + 1) * 64 * 12288;
; #pragma unroll
;             for (int j = 0; j < 4; ++j) { pq[j] = *(const u32x4*)(qsrc + adv + (size_t)j * 16 * 12288); pk[j] = *(const u32x4*)(ksrc + adv + j * 8); }
;             pv = *(const u32x4*)(vsrc + adv);
;             pg[0] = *(const u32x2*)(gsrc + adv); pg[1] = *(const u32x2*)(gsrc + adv + 16);
;         }
;         __syncthreads();
;         bf16x8 qa[8];
;         {
;             f32x4 sacc[2] = {{0.f, 0.f, 0.f, 0.f}, {0.f, 0.f, 0.f, 0.f}};
; #pragma unroll
;             for (int ks = 0; ks < 8; ++ks) qa[ks] = *(const bf16x8*)(Qs + (16 * mi + fr) * QS + ks * 32 + fq * 8);
; #pragma unroll
;             for (int ks = 0; ks < 8; ++ks) {
; #pragma unroll
;                 for (int t = 0; t < 2; ++t) { const bf16x8 bf = *(const bf16x8*)(Ks + (16 * (ni0 + t) + fr) * QS + ks * 32 + fq * 8);
;                     sacc[t] = __builtin_amdgcn_mfma_f32_16x16x32_bf16(bf, qa[ks], sacc[t], 0, 0, 0); }
;             }
.LBB0_179:
	s_barrier
	s_waitcnt vmcnt(3)
	ds_write_b128 v179, v[16:19]
	s_waitcnt vmcnt(6)
	ds_write_b128 v150, v[28:31] offset:33792
	ds_write_b16 v151, v28
	ds_write_b16_d16_hi v175, v28 offset:144
	ds_write_b16 v151, v29 offset:288
	ds_write_b16_d16_hi v174, v29 offset:144
	ds_write_b16 v151, v30 offset:576
	ds_write_b16_d16_hi v173, v30 offset:144
	ds_write_b16 v151, v31 offset:864
	ds_write_b16_d16_hi v171, v31 offset:144
	s_waitcnt vmcnt(5)
	ds_write_b128 v179, v[36:39] offset:8448
	ds_write_b128 v150, v[12:15] offset:33808
	ds_write_b16 v151, v12 offset:1152
	ds_write_b16_d16_hi v170, v12 offset:144
	ds_write_b16 v151, v13 offset:1440
	ds_write_b16_d16_hi v169, v13 offset:144
	ds_write_b16 v151, v14 offset:1728
	ds_write_b16_d16_hi v167, v14 offset:144
	ds_write_b16 v151, v15 offset:2016
	ds_write_b16_d16_hi v166, v15 offset:144
	s_waitcnt vmcnt(4)
	ds_write_b128 v179, v[32:35] offset:16896
	ds_write_b128 v150, v[8:11] offset:33824
	ds_write_b16 v151, v8 offset:2304
	ds_write_b16_d16_hi v164, v8 offset:144
	ds_write_b16 v151, v9 offset:2592
	ds_write_b16_d16_hi v163, v9 offset:144
	ds_write_b16 v151, v10 offset:2880
	ds_write_b16_d16_hi v162, v10 offset:144
	ds_write_b16 v151, v11 offset:3168
	ds_write_b16_d16_hi v161, v11 offset:144
	s_waitcnt vmcnt(3)
	ds_write_b128 v179, v[24:27] offset:25344
	ds_write_b128 v150, v[4:7] offset:33840
	ds_write_b16 v151, v4 offset:3456
	ds_write_b16_d16_hi v159, v4 offset:144
	ds_write_b16 v151, v5 offset:3744
	ds_write_b16_d16_hi v157, v5 offset:144
	ds_write_b16 v151, v6 offset:4032
	ds_write_b16_d16_hi v155, v6 offset:144
	ds_write_b16 v151, v7 offset:4320
	ds_write_b16_d16_hi v153, v7 offset:144
	s_waitcnt vmcnt(1)
	ds_write_b16 v152, v20
	ds_write_b16_d16_hi v160, v20 offset:144
	ds_write_b16 v152, v21 offset:288
	ds_write_b16_d16_hi v158, v21 offset:144
	ds_write_b16 v152, v22 offset:576
	ds_write_b16_d16_hi v156, v22 offset:144
	ds_write_b16 v152, v23 offset:864
	ds_write_b16_d16_hi v154, v23 offset:144
	v_cvt_pk_bf16_f32 v4, v52, v53
	v_cvt_pk_bf16_f32 v5, v54, v55
	ds_write_b64 v165, v[4:5]
	v_cvt_pk_bf16_f32 v4, v40, v41
	v_cvt_pk_bf16_f32 v5, v42, v43
	ds_write_b64 v165, v[4:5] offset:32
	v_cvt_pk_bf16_f32 v4, v56, v57
	v_cvt_pk_bf16_f32 v5, v58, v59
	ds_write_b64 v165, v[4:5] offset:8448
	v_cvt_pk_bf16_f32 v4, v44, v45
	v_cvt_pk_bf16_f32 v5, v46, v47
	ds_write_b64 v165, v[4:5] offset:8480
	v_cvt_pk_bf16_f32 v4, v60, v61
	v_cvt_pk_bf16_f32 v5, v62, v63
	ds_write_b64 v165, v[4:5] offset:16896
	v_cvt_pk_bf16_f32 v4, v48, v49
	v_cvt_pk_bf16_f32 v5, v50, v51
	ds_write_b64 v165, v[4:5] offset:16928
	v_cvt_pk_bf16_f32 v4, v64, v65
	v_cvt_pk_bf16_f32 v5, v66, v67
	ds_write_b64 v165, v[4:5] offset:25344
	v_cvt_pk_bf16_f32 v4, v0, v1
	v_lshl_add_u64 v[20:21], s[56:57], 0, v[126:127]
	s_mov_b32 s0, 0x1d180000
	v_cvt_pk_bf16_f32 v5, v2, v3
	ds_write_b64 v165, v[4:5] offset:25376
	v_add_co_u32_e64 v4, s[0:1], s0, v20
	s_nop 1
	v_addc_co_u32_e64 v5, s[0:1], 0, v21, s[0:1]
	s_mov_b32 s0, 0x1d1e0000
	global_load_dwordx4 v[16:19], v[4:5], off
	s_nop 0
	v_add_co_u32_e64 v22, s[0:1], s0, v20
	v_lshl_add_u64 v[68:69], s[56:57], 0, v[114:115]
	s_nop 0
	v_addc_co_u32_e64 v23, s[0:1], 0, v21, s[0:1]
	s_mov_b32 s0, 0x1d240000
	global_load_dwordx4 v[36:39], v[22:23], off
	v_add_co_u32_e64 v22, s[0:1], s0, v20
	v_add_u32_e32 v183, v168, v177
	s_nop 0
	v_addc_co_u32_e64 v23, s[0:1], 0, v21, s[0:1]
	s_mov_b32 s0, 0x1d2a0000
	s_nop 0
	v_add_co_u32_e64 v20, s[0:1], s0, v20
	global_load_dwordx4 v[32:35], v[22:23], off
	s_nop 0
	v_addc_co_u32_e64 v21, s[0:1], 0, v21, s[0:1]
	s_mov_b32 s0, 0x1d184000
	s_nop 0
	v_add_co_u32_e64 v68, s[0:1], s0, v68
	global_load_dwordx4 v[24:27], v[20:21], off
	s_nop 0
	v_addc_co_u32_e64 v69, s[0:1], 0, v69, s[0:1]
	v_mov_b64_e32 v[134:135], v[110:111]
	v_mov_b64_e32 v[132:133], v[108:109]
	s_nop 0
	global_load_dwordx2 v[110:111], v[68:69], off
	global_load_dwordx2 v[108:109], v[68:69], off offset:32
	s_waitcnt lgkmcnt(0)
	s_barrier
	ds_read_b128 v[96:99], v149
	ds_read_b128 v[92:95], v149 offset:64
	ds_read_b128 v[88:91], v149 offset:128
	ds_read_b128 v[84:87], v149 offset:192
	ds_read_b128 v[80:83], v149 offset:256
	ds_read_b128 v[76:79], v149 offset:320
	ds_read_b128 v[72:75], v149 offset:384
	ds_read_b128 v[68:71], v149 offset:448
	v_add_u32_e32 v182, v168, v178
	ds_read_b128 v[208:211], v183 offset:33792
	ds_read_b128 v[212:215], v182 offset:33792
	ds_read_b128 v[216:219], v183 offset:33856
	ds_read_b128 v[220:223], v182 offset:33856
	ds_read_b128 v[224:227], v183 offset:33920
	ds_read_b128 v[236:239], v182 offset:33920
	ds_read_b128 v[240:243], v183 offset:33984
	v_lshl_add_u64 v[252:253], s[56:57], 0, v[128:129]
	v_lshl_add_u64 v[190:191], s[56:57], 0, v[130:131]
	global_load_dwordx4 v[4:7], v[252:253], off offset:16
	global_load_dwordx4 v[8:11], v[252:253], off
	s_waitcnt lgkmcnt(6)
	v_mfma_f32_16x16x32_bf16 v[184:187], v[208:211], v[96:99], 0
	ds_read_b128 v[244:247], v182 offset:33984
	s_waitcnt lgkmcnt(6)
	v_mfma_f32_16x16x32_bf16 v[192:195], v[212:215], v[96:99], 0
	ds_read_b128 v[208:211], v183 offset:34048
	s_waitcnt lgkmcnt(6)
	v_mfma_f32_16x16x32_bf16 v[184:187], v[216:219], v[92:95], v[184:187]
	ds_read_b128 v[212:215], v182 offset:34048
	s_waitcnt lgkmcnt(6)
	v_mfma_f32_16x16x32_bf16 v[192:195], v[220:223], v[92:95], v[192:195]
	ds_read_b128 v[216:219], v183 offset:34112
	s_waitcnt lgkmcnt(6)
	v_mfma_f32_16x16x32_bf16 v[184:187], v[224:227], v[88:91], v[184:187]
	ds_read_b128 v[220:223], v182 offset:34112
	s_waitcnt lgkmcnt(6)
	v_mfma_f32_16x16x32_bf16 v[192:195], v[236:239], v[88:91], v[192:195]
	ds_read_b128 v[224:227], v183 offset:34176
	s_waitcnt lgkmcnt(6)
; __device__ __forceinline__ void ret_phase(const Params& p, unsigned char* shm, float* rssq) {
;     ...
;             for (int ks = 0; ks < 8; ++ks) {
; #pragma unroll
;                 for (int t = 0; t < 2; ++t) { const bf16x8 bf = *(const bf16x8*)(Ks + (16 * (ni0 + t) + fr) * QS + ks * 32 + fq * 8);
;                     sacc[t] = __builtin_amdgcn_mfma_f32_16x16x32_bf16(bf, qa[ks], sacc[t], 0, 0, 0); }
;             }
; #pragma unroll
;             for (int t = 0; t < 2; ++t) { u32x2 w; w.x = cvt_pk_bf16(sacc[t][0] * idec[t][0], sacc[t][1] * idec[t][1]); w.y = cvt_pk_bf16(sacc[t][2] * idec[t][2], sacc[t][3] * idec[t][3]);
;                 *(u32x2*)(Ss + (16 * mi + fr) * TS + 16 * (ni0 + t) + 4 * fq) = w; }
;         }
;         __syncthreads();
;         {
;             f32x4 oi[2] = {{0.f, 0.f, 0.f, 0.f}, {0.f, 0.f, 0.f, 0.f}}, oc[2] = {{0.f, 0.f, 0.f, 0.f}, {0.f, 0.f, 0.f, 0.f}};
; #pragma unroll
;             for (int ks = 0; ks < 2; ++ks) {
;                 const bf16x8 af = *(const bf16x8*)(Ss + (16 * mi + fr) * TS + ks * 32 + fq * 8);
; #pragma unroll
;                 for (int t = 0; t < 2; ++t) { const bf16x8 bf = *(const bf16x8*)(VTs + (16 * (ni0 + t) + fr) * TS + ks * 32 + fq * 8);
;                     oi[t] = __builtin_amdgcn_mfma_f32_16x16x32_bf16(bf, af, oi[t], 0, 0, 0); }
;             }
; #pragma unroll
;             for (int ks = 0; ks < 8; ++ks) {
; #pragma unroll
;                 for (int t = 0; t < 2; ++t) { const bf16x8 bf = *(const bf16x8*)(RTs + (16 * (ni0 + t) + fr) * QS + ks * 32 + fq * 8);
;                     oc[t] = __builtin_amdgcn_mfma_f32_16x16x32_bf16(bf, qa[ks], oc[t], 0, 0, 0); }
;             }
;             const size_t tok = tokb + (size_t)ch * 64 + 16 * mi + fr;
;             float sq = 0.f;
; #pragma unroll
;             for (int t = 0; t < 2; ++t) {
;                 const int e = sl * 64 + 16 * (ni0 + t) + 4 * fq;
;                 const u32x2 gw = cg2[t];
;                 f32x4 ov = oi[t] + oc[t] * qdec;
;                 sq += ov[0] * ov[0] + ov[1] * ov[1] + ov[2] * ov[2] + ov[3] * ov[3];
;                 u32x2 w; w.x = cvt_pk_bf16(ov[0] * bflo(gw.x), ov[1] * bfhi(gw.x)); w.y = cvt_pk_bf16(ov[2] * bflo(gw.y), ov[3] * bfhi(gw.y));
;                 *(u32x2*)(ao + tok * 4096 + h * 512 + e) = w;
;             }
;             sq += __shfl_xor(sq, 16); sq += __shfl_xor(sq, 32);
	v_mfma_f32_16x16x32_bf16 v[184:187], v[240:243], v[84:87], v[184:187]
	ds_read_b128 v[236:239], v182 offset:34176
	s_waitcnt lgkmcnt(6)
	v_mfma_f32_16x16x32_bf16 v[192:195], v[244:247], v[84:87], v[192:195]
	global_load_dwordx4 v[12:15], v[252:253], off offset:-16
	global_load_dwordx4 v[28:31], v[252:253], off offset:-32
	ds_read_b128 v[240:243], v183 offset:34240
	s_waitcnt lgkmcnt(6)
	v_mfma_f32_16x16x32_bf16 v[184:187], v[208:211], v[80:83], v[184:187]
	ds_read_b128 v[244:247], v182 offset:34240
	s_waitcnt lgkmcnt(6)
	v_mfma_f32_16x16x32_bf16 v[192:195], v[212:215], v[80:83], v[192:195]
	s_waitcnt lgkmcnt(5)
	v_mfma_f32_16x16x32_bf16 v[184:187], v[216:219], v[76:79], v[184:187]
	s_waitcnt lgkmcnt(4)
	v_mfma_f32_16x16x32_bf16 v[192:195], v[220:223], v[76:79], v[192:195]
	global_load_dwordx4 v[20:23], v[190:191], off
	s_waitcnt lgkmcnt(3)
	v_mfma_f32_16x16x32_bf16 v[184:187], v[224:227], v[72:75], v[184:187]
	s_waitcnt lgkmcnt(2)
	v_mfma_f32_16x16x32_bf16 v[192:195], v[236:239], v[72:75], v[192:195]
	s_waitcnt lgkmcnt(1)
	v_mfma_f32_16x16x32_bf16 v[184:187], v[240:243], v[68:71], v[184:187]
	s_waitcnt lgkmcnt(0)
	v_mfma_f32_16x16x32_bf16 v[192:195], v[244:247], v[68:71], v[192:195]
	s_nop 7
	v_mul_f32_e32 v113, v138, v184
	v_mul_f32_e32 v184, v139, v185
	v_mul_f32_e32 v185, v141, v187
	v_cvt_pk_bf16_f32 v184, v113, v184
	v_mul_f32_e32 v113, v140, v186
	v_cvt_pk_bf16_f32 v185, v113, v185
	v_add_u32_e32 v186, v172, v116
	ds_write_b64 v186, v[184:185]
	s_nop 2
	v_mul_f32_e32 v113, v142, v192
	v_mul_f32_e32 v184, v143, v193
	v_mul_f32_e32 v185, v145, v195
	v_cvt_pk_bf16_f32 v184, v113, v184
	v_mul_f32_e32 v113, v144, v194
	v_cvt_pk_bf16_f32 v185, v113, v185
	ds_write_b64 v148, v[184:185]
	s_waitcnt lgkmcnt(0)
	s_barrier
	v_add_u32_e32 v185, v176, v177
	v_add_u32_e32 v184, v176, v178
	ds_read_b128 v[200:203], v117
	ds_read_b128 v[208:211], v147
	ds_read_b128 v[212:215], v146
	ds_read_b128 v[204:207], v117 offset:64
	ds_read_b128 v[216:219], v147 offset:64
	ds_read_b128 v[220:223], v146 offset:64
	ds_read_b128 v[224:227], v185
	ds_read_b128 v[236:239], v184
	s_waitcnt lgkmcnt(6)
	v_mfma_f32_16x16x32_bf16 v[196:199], v[208:211], v[200:203], 0
	ds_read_b128 v[240:243], v185 offset:64
	s_waitcnt lgkmcnt(6)
	v_mfma_f32_16x16x32_bf16 v[192:195], v[212:215], v[200:203], 0
	ds_read_b128 v[244:247], v184 offset:64
	ds_read_b128 v[208:211], v185 offset:128
	s_waitcnt lgkmcnt(6)
	v_mfma_f32_16x16x32_bf16 v[196:199], v[216:219], v[204:207], v[196:199]
	ds_read_b128 v[212:215], v184 offset:128
	s_waitcnt lgkmcnt(6)
	v_mfma_f32_16x16x32_bf16 v[192:195], v[220:223], v[204:207], v[192:195]
	ds_read_b128 v[216:219], v185 offset:192
	s_waitcnt lgkmcnt(6)
	v_mfma_f32_16x16x32_bf16 v[248:251], v[224:227], v[96:99], 0
	ds_read_b128 v[220:223], v184 offset:192
	s_waitcnt lgkmcnt(6)
	v_mfma_f32_16x16x32_bf16 v[230:233], v[236:239], v[96:99], 0
	ds_read_b128 v[224:227], v185 offset:256
	s_waitcnt lgkmcnt(6)
	v_mfma_f32_16x16x32_bf16 v[248:251], v[240:243], v[92:95], v[248:251]
	ds_read_b128 v[236:239], v184 offset:256
	s_waitcnt lgkmcnt(6)
	v_mfma_f32_16x16x32_bf16 v[230:233], v[244:247], v[92:95], v[230:233]
	ds_read_b128 v[240:243], v185 offset:320
	s_waitcnt lgkmcnt(6)
	v_mfma_f32_16x16x32_bf16 v[248:251], v[208:211], v[88:91], v[248:251]
	ds_read_b128 v[244:247], v184 offset:320
	s_waitcnt lgkmcnt(6)
	v_mfma_f32_16x16x32_bf16 v[230:233], v[212:215], v[88:91], v[230:233]
	ds_read_b128 v[208:211], v185 offset:384
	s_waitcnt lgkmcnt(6)
	v_mfma_f32_16x16x32_bf16 v[248:251], v[216:219], v[84:87], v[248:251]
	ds_read_b128 v[212:215], v184 offset:384
	s_waitcnt lgkmcnt(6)
	v_mfma_f32_16x16x32_bf16 v[230:233], v[220:223], v[84:87], v[230:233]
	ds_read_b128 v[216:219], v185 offset:448
	s_waitcnt lgkmcnt(6)
	v_mfma_f32_16x16x32_bf16 v[248:251], v[224:227], v[80:83], v[248:251]
	ds_read_b128 v[220:223], v184 offset:448
	s_waitcnt lgkmcnt(6)
	v_mfma_f32_16x16x32_bf16 v[230:233], v[236:239], v[80:83], v[230:233]
	s_waitcnt lgkmcnt(5)
	v_mfma_f32_16x16x32_bf16 v[248:251], v[240:243], v[76:79], v[248:251]
	s_waitcnt lgkmcnt(4)
	v_mfma_f32_16x16x32_bf16 v[230:233], v[244:247], v[76:79], v[230:233]
	s_waitcnt lgkmcnt(3)
	v_mfma_f32_16x16x32_bf16 v[248:251], v[208:211], v[72:75], v[248:251]
	s_waitcnt lgkmcnt(2)
	v_mfma_f32_16x16x32_bf16 v[230:233], v[212:215], v[72:75], v[230:233]
	s_waitcnt lgkmcnt(1)
	v_mfma_f32_16x16x32_bf16 v[76:79], v[216:219], v[68:71], v[248:251]
	s_waitcnt lgkmcnt(0)
	v_mfma_f32_16x16x32_bf16 v[68:71], v[220:223], v[68:71], v[230:233]
	s_nop 7
	v_fma_f32 v74, v104, v76, v196
	v_fma_f32 v75, v105, v77, v197
	v_lshlrev_b32_e32 v77, 16, v134
	v_mul_f32_e32 v76, v75, v75
	v_fmac_f32_e32 v76, v74, v74
	v_mul_f32_e32 v74, v74, v77
	v_and_b32_e32 v77, 0xffff0000, v134
	v_mul_f32_e32 v75, v75, v77
	v_pk_fma_f32 v[72:73], v[106:107], v[78:79], v[198:199]
	v_cvt_pk_bf16_f32 v74, v74, v75
	v_lshlrev_b32_e32 v75, 16, v135
	v_fmac_f32_e32 v76, v72, v72
	v_mul_f32_e32 v72, v72, v75
	v_and_b32_e32 v75, 0xffff0000, v135
	v_fmac_f32_e32 v76, v73, v73
	v_mul_f32_e32 v73, v73, v75
	v_cvt_pk_bf16_f32 v75, v72, v73
	v_lshl_add_u64 v[72:73], s[56:57], 0, v[122:123]
	v_pk_fma_f32 v[68:69], v[104:105], v[68:69], v[192:193]
	global_store_dwordx2 v[72:73], v[74:75], off
	v_mul_f32_e32 v72, v69, v69
	v_lshlrev_b32_e32 v73, 16, v132
	v_fmac_f32_e32 v72, v68, v68
	v_mul_f32_e32 v68, v68, v73
	v_and_b32_e32 v73, 0xffff0000, v132
	v_mul_f32_e32 v69, v69, v73
	v_pk_fma_f32 v[70:71], v[106:107], v[70:71], v[194:195]
	v_cvt_pk_bf16_f32 v68, v68, v69
	v_lshlrev_b32_e32 v69, 16, v133
	v_fmac_f32_e32 v72, v70, v70
	v_mul_f32_e32 v69, v70, v69
	v_and_b32_e32 v70, 0xffff0000, v133
	v_mul_f32_e32 v70, v71, v70
	v_fmac_f32_e32 v72, v71, v71
	v_cvt_pk_bf16_f32 v69, v69, v70
	v_lshl_add_u64 v[70:71], s[56:57], 0, v[124:125]
	global_store_dwordx2 v[70:71], v[68:69], off
	v_and_b32_e32 v69, 64, v229
	v_xor_b32_e32 v68, 16, v229
	v_add_u32_e32 v69, 64, v69
	v_cmp_lt_i32_e64 s[0:1], v68, v69
	v_add_f32_e32 v72, v76, v72
	v_xor_b32_e32 v71, 32, v229
	v_cndmask_b32_e64 v68, v229, v68, s[0:1]
	v_lshlrev_b32_e32 v68, 2, v68
	ds_bpermute_b32 v70, v68, v72
	v_cmp_lt_i32_e64 s[0:1], v71, v69
	s_waitcnt lgkmcnt(0)
	v_add_f32_e32 v70, v72, v70
	v_cndmask_b32_e64 v69, v229, v71, s[0:1]
	v_lshlrev_b32_e32 v69, 2, v69
	ds_bpermute_b32 v71, v69, v70
	s_and_saveexec_b64 s[0:1], vcc
	s_cbranch_execz .LBB0_178
	s_waitcnt lgkmcnt(0)
	v_add_f32_e32 v72, v70, v71
	v_lshl_add_u64 v[70:71], v[120:121], 0, s[10:11]
	global_atomic_add_f32 v[70:71], v72, off
	s_branch .LBB0_178
